# scan chunk loop: DMA two chunks ahead (3 raw buffers, no mid-step drain) + output-store LDS reads batched + V-transpose LDS reads batched (one wait instead of four)
# baseline (speedup 1.0000x reference)
.LBB0_406:
	s_or_b64 exec, exec, vcc
	s_and_saveexec_b64 vcc, s[42:43]
	s_cbranch_execz .LBB0_408
	v_add3_u32 v83, s20, v137, v128
	ds_read_u16 v80, v83 offset:16640
	ds_read_u16 v81, v83 offset:16768
	ds_read_u16 v85, v83 offset:16896
	ds_read_u16 v86, v83 offset:17024
	ds_read_u16 v87, v83 offset:17152
	ds_read_u16 v88, v83 offset:17280
	ds_read_u16 v89, v83 offset:17408
	ds_read_u16 v90, v83 offset:17536
	s_waitcnt lgkmcnt(6)
	v_lshl_or_b32 v80, v81, 16, v80
	s_waitcnt lgkmcnt(4)
	v_lshl_or_b32 v81, v86, 16, v85
	s_waitcnt lgkmcnt(2)
	v_lshl_or_b32 v82, v88, 16, v87
	s_waitcnt lgkmcnt(0)
	v_lshl_or_b32 v83, v90, 16, v89
	ds_write_b128 v174, v[80:83]
